# weight prefetch at seams: while waiting at the seam before P4/P5/P6/P7, waves 1..4 touch this workgroup's slice of the next phase's bf16 weight matrix (stored nt, else first use comes from HBM); on to
# speedup vs baseline: 1.0196x; 1.0074x over previous
.LBB0_874:
	s_cmp_gt_i32 s95, 4
	s_cselect_b64 s[0:1], -1, 0
	s_and_b64 s[2:3], s[4:5], s[0:1]
	s_andn2_b64 vcc, exec, s[2:3]
	s_cbranch_vccnz .LBB0_924
	s_waitcnt vmcnt(0)
	v_cmp_eq_u32_e32 vcc, 0, v0
	s_waitcnt vmcnt(63) expcnt(7) lgkmcnt(15)
	s_barrier
	v_lshrrev_b32_e32 v1, 6, v0
	v_and_b32_e32 v2, 63, v0
	v_add_u32_e32 v4, -1, v1
	v_cmp_gt_u32_e32 vcc, 1, v4
	s_and_saveexec_b64 s[8:9], vcc
	s_cbranch_execz .Lwpf3
	v_readlane_b32 s2, v253, 20
	s_nop 3
	s_mul_i32 s2, s2, 1
	v_add_u32_e32 v1, s2, v4
	v_mul_u32_u24_e32 v1, 0x2000, v1
	v_lshl_add_u32 v1, v2, 7, v1
	s_add_u32 s2, s44, 0xa00000
	s_addc_u32 s3, s45, 0
	global_load_dword v3, v1, s[2:3]
.Lwpf3:
	s_or_b64 exec, exec, s[8:9]
	v_cmp_eq_u32_e32 vcc, 0, v0
	s_and_saveexec_b64 s[4:5], vcc
	s_cbranch_execz .LBB0_923
	v_mov_b32_e32 v1, s82
	s_waitcnt vmcnt(0) expcnt(0) lgkmcnt(0)
	ds_read_b32 v3, v1
	ds_read_b32 v1, v1 offset:4
	s_waitcnt lgkmcnt(1)
	v_cmp_ne_u32_e32 vcc, 0, v3
	s_cbranch_vccnz .LBB0_891
	v_readlane_b32 s6, v253, 0
	v_readlane_b32 s7, v253, 1
	s_load_dwordx2 s[2:3], s[6:7], 0x4
	s_add_u32 s6, s44, 0x1200
	s_addc_u32 s7, s45, 0
	s_add_u32 s8, s44, 0x1400
	s_addc_u32 s9, s45, 0
	s_add_u32 s10, s44, 0x1500
	s_addc_u32 s11, s45, 0
	s_add_u32 s12, s44, 0x1600
	s_addc_u32 s13, s45, 0
	s_add_u32 s14, s44, 0x1700
	s_addc_u32 s15, s45, 0
	s_add_u32 s16, s44, 0x1800
	s_addc_u32 s17, s45, 0
	s_add_u32 s18, s44, 0x1900
	s_addc_u32 s19, s45, 0
	s_add_u32 s20, s44, 0x1a00
	s_addc_u32 s21, s45, 0
	s_add_u32 s22, s44, 0x1b00
	s_addc_u32 s23, s45, 0
	s_add_u32 s28, s44, 0x1c00
	s_addc_u32 s29, s45, 0
	s_add_u32 s30, s44, 0x1d00
	s_addc_u32 s31, s45, 0
	s_add_u32 s40, s44, 0x1e00
	s_addc_u32 s41, s45, 0
	s_add_u32 s42, s44, 0x1f00
	s_addc_u32 s43, s45, 0
	s_add_u32 s46, s44, 0x2000
	s_addc_u32 s47, s45, 0
	s_add_u32 s48, s44, 0x2100
	s_addc_u32 s49, s45, 0
	s_add_u32 s50, s44, 0x2200
	s_addc_u32 s51, s45, 0
	s_waitcnt lgkmcnt(0)
	s_mul_i32 s2, s2, s96
	s_add_u32 s52, s44, 0x2300
	s_mul_i32 s2, s2, s3
	s_addc_u32 s53, s45, 0
	s_mov_b32 s3, 1
	v_mov_b32_e32 v17, 0
	s_branch .LBB0_879

.LBB0_1081:
	s_cmp_gt_i32 s95, 5
	s_cselect_b64 s[0:1], -1, 0
	s_and_b64 s[2:3], s[4:5], s[0:1]
	s_andn2_b64 vcc, exec, s[2:3]
	s_cbranch_vccnz .LBB0_1131
	s_waitcnt vmcnt(0)
	v_cmp_eq_u32_e32 vcc, 0, v0
	s_waitcnt vmcnt(63) expcnt(7) lgkmcnt(15)
	s_barrier
	v_lshrrev_b32_e32 v1, 6, v0
	v_and_b32_e32 v2, 63, v0
	v_add_u32_e32 v4, -1, v1
	v_cmp_gt_u32_e32 vcc, 1, v4
	s_and_saveexec_b64 s[8:9], vcc
	s_cbranch_execz .Lwpf4
	v_readlane_b32 s2, v253, 20
	s_nop 3
	s_mul_i32 s2, s2, 1
	v_add_u32_e32 v1, s2, v4
	v_mul_u32_u24_e32 v1, 0x2000, v1
	v_lshl_add_u32 v1, v2, 7, v1
	s_add_u32 s2, s44, 0xc00000
	s_addc_u32 s3, s45, 0
	global_load_dword v3, v1, s[2:3]
.Lwpf4:
	s_or_b64 exec, exec, s[8:9]
	v_cmp_eq_u32_e32 vcc, 0, v0
	s_and_saveexec_b64 s[4:5], vcc
	s_cbranch_execz .LBB0_1130
	v_mov_b32_e32 v1, s82
	s_waitcnt vmcnt(0) expcnt(0) lgkmcnt(0)
	ds_read_b32 v3, v1
	ds_read_b32 v1, v1 offset:4
	s_waitcnt lgkmcnt(1)
	v_cmp_ne_u32_e32 vcc, 0, v3
	s_cbranch_vccnz .LBB0_1098
	v_readlane_b32 s6, v253, 0
	v_readlane_b32 s7, v253, 1
	s_load_dwordx2 s[2:3], s[6:7], 0x4
	s_add_u32 s6, s44, 0x1200
	s_addc_u32 s7, s45, 0
	s_add_u32 s8, s44, 0x1400
	s_addc_u32 s9, s45, 0
	s_add_u32 s10, s44, 0x1500
	s_addc_u32 s11, s45, 0
	s_add_u32 s12, s44, 0x1600
	s_addc_u32 s13, s45, 0
	s_add_u32 s14, s44, 0x1700
	s_addc_u32 s15, s45, 0
	s_add_u32 s16, s44, 0x1800
	s_addc_u32 s17, s45, 0
	s_add_u32 s18, s44, 0x1900
	s_addc_u32 s19, s45, 0
	s_add_u32 s20, s44, 0x1a00
	s_addc_u32 s21, s45, 0
	s_add_u32 s22, s44, 0x1b00
	s_addc_u32 s23, s45, 0
	s_add_u32 s28, s44, 0x1c00
	s_addc_u32 s29, s45, 0
	s_add_u32 s30, s44, 0x1d00
	s_addc_u32 s31, s45, 0
	s_add_u32 s36, s44, 0x1e00
	s_addc_u32 s37, s45, 0
	s_add_u32 s38, s44, 0x1f00
	s_addc_u32 s39, s45, 0
	s_add_u32 s40, s44, 0x2000
	s_addc_u32 s41, s45, 0
	s_add_u32 s42, s44, 0x2100
	s_addc_u32 s43, s45, 0
	s_add_u32 s46, s44, 0x2200
	s_addc_u32 s47, s45, 0
	s_waitcnt lgkmcnt(0)
	s_mul_i32 s2, s2, s96
	s_add_u32 s48, s44, 0x2300
	s_mul_i32 s2, s2, s3
	s_addc_u32 s49, s45, 0
	s_mov_b32 s3, 1
	v_mov_b32_e32 v17, 0
	s_branch .LBB0_1086

.LBB0_1175:
	s_cmp_gt_i32 s95, 6
	s_cselect_b64 s[0:1], -1, 0
	s_and_b64 s[2:3], s[6:7], s[0:1]
	s_andn2_b64 vcc, exec, s[2:3]
	s_cbranch_vccnz .LBB0_1225
	s_waitcnt vmcnt(0)
	v_cmp_eq_u32_e32 vcc, 0, v0
	s_waitcnt lgkmcnt(0)
	s_barrier
	v_lshrrev_b32_e32 v1, 6, v0
	v_and_b32_e32 v2, 63, v0
	v_add_u32_e32 v4, -1, v1
	v_cmp_gt_u32_e32 vcc, 4, v4
	s_and_saveexec_b64 s[8:9], vcc
	s_cbranch_execz .Lwpf5
	v_readlane_b32 s2, v253, 20
	s_nop 3
	s_mul_i32 s2, s2, 4
	v_add_u32_e32 v1, s2, v4
	v_mul_u32_u24_e32 v1, 0x8000, v1
	v_lshl_add_u32 v1, v2, 7, v1
	s_add_u32 s2, s44, 0x1d600000
	s_addc_u32 s3, s45, 0
	global_load_dword v3, v1, s[2:3]
	s_add_u32 s2, s2, 0x2000
	s_addc_u32 s3, s3, 0
	global_load_dword v3, v1, s[2:3]
	s_add_u32 s2, s2, 0x2000
	s_addc_u32 s3, s3, 0
	global_load_dword v3, v1, s[2:3]
	s_add_u32 s2, s2, 0x2000
	s_addc_u32 s3, s3, 0
	global_load_dword v3, v1, s[2:3]
.Lwpf5:
	s_or_b64 exec, exec, s[8:9]
	v_cmp_eq_u32_e32 vcc, 0, v0
	s_and_saveexec_b64 s[6:7], vcc
	s_cbranch_execz .LBB0_1224
	v_mov_b32_e32 v1, s82
	s_waitcnt vmcnt(0) expcnt(0) lgkmcnt(0)
	ds_read_b32 v3, v1
	ds_read_b32 v1, v1 offset:4
	s_waitcnt lgkmcnt(1)
	v_cmp_ne_u32_e32 vcc, 0, v3
	s_cbranch_vccnz .LBB0_1192
	v_readlane_b32 s8, v253, 0
	v_readlane_b32 s9, v253, 1
	s_load_dwordx2 s[2:3], s[8:9], 0x4
	s_add_u32 s8, s44, 0x1200
	s_addc_u32 s9, s45, 0
	s_add_u32 s10, s44, 0x1400
	s_addc_u32 s11, s45, 0
	s_add_u32 s12, s44, 0x1500
	s_addc_u32 s13, s45, 0
	s_add_u32 s14, s44, 0x1600
	s_addc_u32 s15, s45, 0
	s_add_u32 s16, s44, 0x1700
	s_addc_u32 s17, s45, 0
	s_add_u32 s18, s44, 0x1800
	s_addc_u32 s19, s45, 0
	s_add_u32 s20, s44, 0x1900
	s_addc_u32 s21, s45, 0
	s_add_u32 s22, s44, 0x1a00
	s_addc_u32 s23, s45, 0
	s_add_u32 s28, s44, 0x1b00
	s_addc_u32 s29, s45, 0
	s_add_u32 s30, s44, 0x1c00
	s_addc_u32 s31, s45, 0
	s_add_u32 s34, s44, 0x1d00
	s_addc_u32 s35, s45, 0
	s_add_u32 s36, s44, 0x1e00
	s_addc_u32 s37, s45, 0
	s_add_u32 s38, s44, 0x1f00
	s_addc_u32 s39, s45, 0
	s_add_u32 s40, s44, 0x2000
	s_addc_u32 s41, s45, 0
	s_add_u32 s42, s44, 0x2100
	s_addc_u32 s43, s45, 0
	s_mov_b64 s[46:47], s[44:45]
	s_add_u32 s44, s46, 0x2200
	s_addc_u32 s45, s47, 0
	s_waitcnt lgkmcnt(0)
	s_mul_i32 s2, s2, s96
	s_add_u32 s46, s46, 0x2300
	s_mul_i32 s2, s2, s3
	s_addc_u32 s47, s47, 0
	s_mov_b32 s3, 1
	v_mov_b32_e32 v17, 0
	s_branch .LBB0_1180

.LBB0_1251:
	s_cmp_gt_i32 s95, 7
	s_cselect_b64 s[4:5], -1, 0
	s_and_b64 s[0:1], s[0:1], s[4:5]
	s_andn2_b64 vcc, exec, s[0:1]
	s_cbranch_vccnz .LBB0_1301
	s_waitcnt vmcnt(0)
	v_cmp_eq_u32_e32 vcc, 0, v0
	s_waitcnt lgkmcnt(0)
	s_barrier
	v_lshrrev_b32_e32 v1, 6, v0
	v_and_b32_e32 v2, 63, v0
	v_add_u32_e32 v4, -1, v1
	v_cmp_gt_u32_e32 vcc, 4, v4
	s_and_saveexec_b64 s[8:9], vcc
	s_cbranch_execz .Lwpf6
	v_readlane_b32 s2, v253, 20
	s_nop 3
	s_mul_i32 s2, s2, 4
	v_add_u32_e32 v1, s2, v4
	v_mul_u32_u24_e32 v1, 0x2000, v1
	v_lshl_add_u32 v1, v2, 7, v1
	s_add_u32 s2, s44, 0x1600000
	s_addc_u32 s3, s45, 0
	global_load_dword v3, v1, s[2:3]
.Lwpf6:
	s_or_b64 exec, exec, s[8:9]
	v_cmp_eq_u32_e32 vcc, 0, v0
	s_and_saveexec_b64 s[0:1], vcc
	s_cbranch_execz .LBB0_1300
	v_mov_b32_e32 v1, s82
	s_waitcnt vmcnt(0) expcnt(0) lgkmcnt(0)
	ds_read_b32 v3, v1
	ds_read_b32 v1, v1 offset:4
	s_waitcnt lgkmcnt(1)
	v_cmp_ne_u32_e32 vcc, 0, v3
	s_cbranch_vccnz .LBB0_1268
	v_readlane_b32 s6, v253, 0
	v_readlane_b32 s7, v253, 1
	s_load_dwordx2 s[2:3], s[6:7], 0x4
	s_add_u32 s6, s44, 0x1200
	s_addc_u32 s7, s45, 0
	s_add_u32 s8, s44, 0x1400
	s_addc_u32 s9, s45, 0
	s_add_u32 s10, s44, 0x1500
	s_addc_u32 s11, s45, 0
	s_add_u32 s12, s44, 0x1600
	s_addc_u32 s13, s45, 0
	s_add_u32 s14, s44, 0x1700
	s_addc_u32 s15, s45, 0
	s_add_u32 s16, s44, 0x1800
	s_addc_u32 s17, s45, 0
	s_add_u32 s18, s44, 0x1900
	s_addc_u32 s19, s45, 0
	s_add_u32 s20, s44, 0x1a00
	s_addc_u32 s21, s45, 0
	s_add_u32 s22, s44, 0x1b00
	s_addc_u32 s23, s45, 0
	s_add_u32 s28, s44, 0x1c00
	s_addc_u32 s29, s45, 0
	s_add_u32 s30, s44, 0x1d00
	s_addc_u32 s31, s45, 0
	s_add_u32 s34, s44, 0x1e00
	s_addc_u32 s35, s45, 0
	s_add_u32 s36, s44, 0x1f00
	s_addc_u32 s37, s45, 0
	s_add_u32 s38, s44, 0x2000
	s_addc_u32 s39, s45, 0
	s_add_u32 s40, s44, 0x2100
	s_addc_u32 s41, s45, 0
	s_add_u32 s42, s44, 0x2200
	s_addc_u32 s43, s45, 0
	s_waitcnt lgkmcnt(0)
	s_mul_i32 s2, s2, s96
	s_add_u32 s44, s44, 0x2300
	s_mul_i32 s2, s2, s3
	s_addc_u32 s45, s45, 0
	s_mov_b32 s3, 1
	v_mov_b32_e32 v17, 0
	s_branch .LBB0_1256
